# skinny sample-row GEMMs re-tiled to 32 rows x 32 cols per CU (less per-CU traffic) on top of v24
# baseline (speedup 1.0000x reference)
.Lsk_p3_loop:
	s_cmpk_lt_i32 s12, 0x100
	s_cbranch_scc0 .Lsk_p3_done
	s_and_b32 s18, s12, 7
	s_lshr_b32 s20, s12, 5
	s_lshl_b32 s20, s20, 3
	s_or_b32 s18, s18, s20
	s_bfe_u32 s19, s12, 0x20003
	s_lshl_b32 s20, s19, 5
	v_add_u32_e32 v28, s20, v21
	s_mul_i32 s21, s13, 0x300
	v_mul_u32_u24_e32 v16, 0x1800, v28
	v_add_u32_e32 v16, s21, v16
	v_lshl_add_u32 v16, v22, 4, v16
	v_add_u32_e32 v17, 0x18000, v16
	s_lshl_b32 s20, s18, 5
	v_add_u32_e32 v29, s20, v21
	v_mul_u32_u24_e32 v18, 0x1800, v29
	v_add_u32_e32 v18, s21, v18
	v_lshl_add_u32 v18, v22, 4, v18
	v_add_u32_e32 v19, 0x18000, v18
	v_lshlrev_b32_e32 v30, 2, v28
	global_load_dword v24, v30, s[4:5] offset:0
	global_load_dword v25, v30, s[4:5] offset:64
	global_load_dwordx4 v[32:35], v18, s[2:3] offset:0
	global_load_dwordx4 v[36:39], v19, s[2:3] offset:0
	global_load_dwordx4 v[40:43], v18, s[2:3] offset:64
	global_load_dwordx4 v[44:47], v19, s[2:3] offset:64
	global_load_dwordx4 v[48:51], v18, s[2:3] offset:128
	global_load_dwordx4 v[52:55], v19, s[2:3] offset:128
	global_load_dwordx4 v[56:59], v18, s[2:3] offset:192
	global_load_dwordx4 v[60:63], v19, s[2:3] offset:192
	global_load_dwordx4 v[64:67], v18, s[2:3] offset:256
	global_load_dwordx4 v[68:71], v19, s[2:3] offset:256
	global_load_dwordx4 v[72:75], v18, s[2:3] offset:320
	global_load_dwordx4 v[76:79], v19, s[2:3] offset:320
	global_load_dwordx4 v[80:83], v18, s[2:3] offset:384
	global_load_dwordx4 v[84:87], v19, s[2:3] offset:384
	global_load_dwordx4 v[88:91], v18, s[2:3] offset:448
	global_load_dwordx4 v[92:95], v19, s[2:3] offset:448
	global_load_dwordx4 v[96:99], v18, s[2:3] offset:512
	global_load_dwordx4 v[100:103], v19, s[2:3] offset:512
	global_load_dwordx4 v[104:107], v18, s[2:3] offset:576
	global_load_dwordx4 v[108:111], v19, s[2:3] offset:576
	global_load_dwordx4 v[112:115], v16, s[0:1] offset:0
	global_load_dwordx4 v[116:119], v17, s[0:1] offset:0
	global_load_dwordx4 v[120:123], v16, s[0:1] offset:64
	global_load_dwordx4 v[124:127], v17, s[0:1] offset:64
	global_load_dwordx4 v[174:177], v16, s[0:1] offset:128
	global_load_dwordx4 v[178:181], v17, s[0:1] offset:128
	global_load_dwordx4 v[182:185], v16, s[0:1] offset:192
	global_load_dwordx4 v[186:189], v17, s[0:1] offset:192
	global_load_dwordx4 v[190:193], v16, s[0:1] offset:256
	global_load_dwordx4 v[194:197], v17, s[0:1] offset:256
	global_load_dwordx4 v[198:201], v16, s[0:1] offset:320
	global_load_dwordx4 v[202:205], v17, s[0:1] offset:320
	s_waitcnt vmcnt(32)
	v_mov_b32_e32 v31, 0x358637bd
	v_fmamk_f32 v24, v24, 0x3a000000, v31
	v_fmamk_f32 v25, v25, 0x3a000000, v31
	s_mov_b32 s20, 0x800000
	v_mul_f32_e32 v31, 0x4b800000, v24
	v_cmp_gt_f32_e32 vcc, s20, v24
	s_nop 1
	v_cndmask_b32_e32 v24, v24, v31, vcc
	v_rsq_f32_e32 v24, v24
	s_nop 0
	v_mul_f32_e32 v31, 0x45800000, v24
	v_cndmask_b32_e32 v24, v24, v31, vcc
	v_mul_f32_e32 v31, 0x4b800000, v25
	v_cmp_gt_f32_e32 vcc, s20, v25
	s_nop 1
	v_cndmask_b32_e32 v25, v25, v31, vcc
	v_rsq_f32_e32 v25, v25
	s_nop 0
	v_mul_f32_e32 v31, 0x45800000, v25
	v_cndmask_b32_e32 v25, v25, v31, vcc
	s_waitcnt vmcnt(11)
	v_mfma_f32_16x16x32_bf16 v[0:3], v[32:35], v[112:115], 0
	s_waitcnt vmcnt(10)
	v_mfma_f32_16x16x32_bf16 v[4:7], v[32:35], v[116:119], 0
	v_mfma_f32_16x16x32_bf16 v[8:11], v[36:39], v[112:115], 0
	v_mfma_f32_16x16x32_bf16 v[12:15], v[36:39], v[116:119], 0
	global_load_dwordx4 v[112:115], v16, s[0:1] offset:384
	global_load_dwordx4 v[116:119], v17, s[0:1] offset:384
	global_load_dwordx4 v[32:35], v18, s[2:3] offset:640
	global_load_dwordx4 v[36:39], v19, s[2:3] offset:640
	s_waitcnt vmcnt(13)
	v_mfma_f32_16x16x32_bf16 v[0:3], v[40:43], v[120:123], v[0:3]
	s_waitcnt vmcnt(12)
	v_mfma_f32_16x16x32_bf16 v[4:7], v[40:43], v[124:127], v[4:7]
	v_mfma_f32_16x16x32_bf16 v[8:11], v[44:47], v[120:123], v[8:11]
	v_mfma_f32_16x16x32_bf16 v[12:15], v[44:47], v[124:127], v[12:15]
	global_load_dwordx4 v[120:123], v16, s[0:1] offset:448
	global_load_dwordx4 v[124:127], v17, s[0:1] offset:448
	global_load_dwordx4 v[40:43], v18, s[2:3] offset:704
	global_load_dwordx4 v[44:47], v19, s[2:3] offset:704
	s_waitcnt vmcnt(15)
	v_mfma_f32_16x16x32_bf16 v[0:3], v[48:51], v[174:177], v[0:3]
	s_waitcnt vmcnt(14)
	v_mfma_f32_16x16x32_bf16 v[4:7], v[48:51], v[178:181], v[4:7]
	v_mfma_f32_16x16x32_bf16 v[8:11], v[52:55], v[174:177], v[8:11]
	v_mfma_f32_16x16x32_bf16 v[12:15], v[52:55], v[178:181], v[12:15]
	global_load_dwordx4 v[174:177], v16, s[0:1] offset:512
	global_load_dwordx4 v[178:181], v17, s[0:1] offset:512
	s_waitcnt vmcnt(15)
	v_mfma_f32_16x16x32_bf16 v[0:3], v[56:59], v[182:185], v[0:3]
	s_waitcnt vmcnt(14)
	v_mfma_f32_16x16x32_bf16 v[4:7], v[56:59], v[186:189], v[4:7]
	v_mfma_f32_16x16x32_bf16 v[8:11], v[60:63], v[182:185], v[8:11]
	v_mfma_f32_16x16x32_bf16 v[12:15], v[60:63], v[186:189], v[12:15]
	global_load_dwordx4 v[182:185], v16, s[0:1] offset:576
	global_load_dwordx4 v[186:189], v17, s[0:1] offset:576
	s_cmp_eq_u32 s13, 5
	s_cbranch_scc0 .Lsk_p3_nomid
	s_nop 7
	s_nop 3
	v_mul_f32_e32 v0, v0, v24
	v_mul_f32_e32 v1, v1, v24
	v_mul_f32_e32 v2, v2, v24
	v_mul_f32_e32 v3, v3, v24
	v_mul_f32_e32 v4, v4, v25
	v_mul_f32_e32 v5, v5, v25
	v_mul_f32_e32 v6, v6, v25
	v_mul_f32_e32 v7, v7, v25
	v_mul_f32_e32 v8, v8, v24
	v_mul_f32_e32 v9, v9, v24
	v_mul_f32_e32 v10, v10, v24
	v_mul_f32_e32 v11, v11, v24
	v_mul_f32_e32 v12, v12, v25
	v_mul_f32_e32 v13, v13, v25
	v_mul_f32_e32 v14, v14, v25
	v_mul_f32_e32 v15, v15, v25
	s_nop 1
.Lsk_p3_nomid:
	s_waitcnt vmcnt(15)
	v_mfma_f32_16x16x32_bf16 v[0:3], v[64:67], v[190:193], v[0:3]
	s_waitcnt vmcnt(14)
	v_mfma_f32_16x16x32_bf16 v[4:7], v[64:67], v[194:197], v[4:7]
	v_mfma_f32_16x16x32_bf16 v[8:11], v[68:71], v[190:193], v[8:11]
	v_mfma_f32_16x16x32_bf16 v[12:15], v[68:71], v[194:197], v[12:15]
	global_load_dwordx4 v[190:193], v16, s[0:1] offset:640
	global_load_dwordx4 v[194:197], v17, s[0:1] offset:640
	s_waitcnt vmcnt(15)
	v_mfma_f32_16x16x32_bf16 v[0:3], v[72:75], v[198:201], v[0:3]
	s_waitcnt vmcnt(14)
	v_mfma_f32_16x16x32_bf16 v[4:7], v[72:75], v[202:205], v[4:7]
	v_mfma_f32_16x16x32_bf16 v[8:11], v[76:79], v[198:201], v[8:11]
	v_mfma_f32_16x16x32_bf16 v[12:15], v[76:79], v[202:205], v[12:15]
	global_load_dwordx4 v[198:201], v16, s[0:1] offset:704
	global_load_dwordx4 v[202:205], v17, s[0:1] offset:704
	s_waitcnt vmcnt(15)
	v_mfma_f32_16x16x32_bf16 v[0:3], v[80:83], v[112:115], v[0:3]
	s_waitcnt vmcnt(14)
	v_mfma_f32_16x16x32_bf16 v[4:7], v[80:83], v[116:119], v[4:7]
	v_mfma_f32_16x16x32_bf16 v[8:11], v[84:87], v[112:115], v[8:11]
	v_mfma_f32_16x16x32_bf16 v[12:15], v[84:87], v[116:119], v[12:15]
	s_waitcnt vmcnt(11)
	v_mfma_f32_16x16x32_bf16 v[0:3], v[88:91], v[120:123], v[0:3]
	s_waitcnt vmcnt(10)
	v_mfma_f32_16x16x32_bf16 v[4:7], v[88:91], v[124:127], v[4:7]
	v_mfma_f32_16x16x32_bf16 v[8:11], v[92:95], v[120:123], v[8:11]
	v_mfma_f32_16x16x32_bf16 v[12:15], v[92:95], v[124:127], v[12:15]
	s_waitcnt vmcnt(7)
	v_mfma_f32_16x16x32_bf16 v[0:3], v[96:99], v[174:177], v[0:3]
	s_waitcnt vmcnt(6)
	v_mfma_f32_16x16x32_bf16 v[4:7], v[96:99], v[178:181], v[4:7]
	v_mfma_f32_16x16x32_bf16 v[8:11], v[100:103], v[174:177], v[8:11]
	v_mfma_f32_16x16x32_bf16 v[12:15], v[100:103], v[178:181], v[12:15]
	s_waitcnt vmcnt(5)
	v_mfma_f32_16x16x32_bf16 v[0:3], v[104:107], v[182:185], v[0:3]
	s_waitcnt vmcnt(4)
	v_mfma_f32_16x16x32_bf16 v[4:7], v[104:107], v[186:189], v[4:7]
	v_mfma_f32_16x16x32_bf16 v[8:11], v[108:111], v[182:185], v[8:11]
	v_mfma_f32_16x16x32_bf16 v[12:15], v[108:111], v[186:189], v[12:15]
	s_waitcnt vmcnt(3)
	v_mfma_f32_16x16x32_bf16 v[0:3], v[32:35], v[190:193], v[0:3]
	s_waitcnt vmcnt(2)
	v_mfma_f32_16x16x32_bf16 v[4:7], v[32:35], v[194:197], v[4:7]
	v_mfma_f32_16x16x32_bf16 v[8:11], v[36:39], v[190:193], v[8:11]
	v_mfma_f32_16x16x32_bf16 v[12:15], v[36:39], v[194:197], v[12:15]
	s_waitcnt vmcnt(1)
	v_mfma_f32_16x16x32_bf16 v[0:3], v[40:43], v[198:201], v[0:3]
	s_waitcnt vmcnt(0)
	v_mfma_f32_16x16x32_bf16 v[4:7], v[40:43], v[202:205], v[4:7]
	v_mfma_f32_16x16x32_bf16 v[8:11], v[44:47], v[198:201], v[8:11]
	v_mfma_f32_16x16x32_bf16 v[12:15], v[44:47], v[202:205], v[12:15]
	s_cmp_lt_u32 s13, 5
	s_cbranch_scc0 .Lsk_p3_noend
	s_nop 7
	s_nop 3
	v_mul_f32_e32 v0, v0, v24
	v_mul_f32_e32 v1, v1, v24
	v_mul_f32_e32 v2, v2, v24
	v_mul_f32_e32 v3, v3, v24
	v_mul_f32_e32 v4, v4, v25
	v_mul_f32_e32 v5, v5, v25
	v_mul_f32_e32 v6, v6, v25
	v_mul_f32_e32 v7, v7, v25
	v_mul_f32_e32 v8, v8, v24
	v_mul_f32_e32 v9, v9, v24
	v_mul_f32_e32 v10, v10, v24
	v_mul_f32_e32 v11, v11, v24
	v_mul_f32_e32 v12, v12, v25
	v_mul_f32_e32 v13, v13, v25
	v_mul_f32_e32 v14, v14, v25
	v_mul_f32_e32 v15, v15, v25
	s_nop 1
.Lsk_p3_noend:
	s_lshl_b32 s20, s13, 12
	v_lshl_add_u32 v31, v23, 4, s20
	s_nop 7
	s_nop 3
	ds_write_b128 v31, v[0:3]
	ds_write_b128 v31, v[4:7] offset:1024
	ds_write_b128 v31, v[8:11] offset:2048
	ds_write_b128 v31, v[12:15] offset:3072
	s_lshl_b32 s20, s19, 5
	s_and_b32 s21, s13, 1
	s_lshl_b32 s21, s21, 4
	s_add_i32 s20, s20, s21
	v_add_u32_e32 v28, s20, v21
	s_lshl_b32 s21, s18, 5
	s_lshr_b32 s20, s13, 1
	s_lshl_b32 s20, s20, 4
	s_add_i32 s21, s21, s20
	v_lshl_add_u32 v29, v22, 2, s21
	v_lshl_add_u32 v29, v28, 11, v29
	s_lshl_b32 s20, s13, 10
	v_lshl_add_u32 v30, v23, 4, s20
	s_waitcnt lgkmcnt(0)
	s_barrier
	s_cmp_lt_u32 s13, 4
	s_cbranch_scc0 .Lsk_p3_skip
	v_lshlrev_b32_e32 v64, 2, v29
	global_load_dwordx4 v[68:71], v64, s[6:7]
	v_lshlrev_b32_e32 v65, 1, v29
	ds_read_b128 v[32:35], v30
	ds_read_b128 v[36:39], v30 offset:4096
	ds_read_b128 v[40:43], v30 offset:8192
	ds_read_b128 v[44:47], v30 offset:12288
	ds_read_b128 v[48:51], v30 offset:16384
	ds_read_b128 v[52:55], v30 offset:20480
	ds_read_b128 v[56:59], v30 offset:24576
	ds_read_b128 v[60:63], v30 offset:28672
	s_waitcnt lgkmcnt(7)
	v_pk_add_f32 v[34:35], v[34:35], 0 op_sel_hi:[1,0]
	v_pk_add_f32 v[32:33], v[32:33], 0 op_sel_hi:[1,0]
	s_waitcnt lgkmcnt(6)
	v_pk_add_f32 v[34:35], v[34:35], v[38:39]
	v_pk_add_f32 v[32:33], v[32:33], v[36:37]
	s_waitcnt lgkmcnt(5)
	v_pk_add_f32 v[34:35], v[34:35], v[42:43]
	v_pk_add_f32 v[32:33], v[32:33], v[40:41]
	s_waitcnt lgkmcnt(4)
	v_pk_add_f32 v[34:35], v[34:35], v[46:47]
	v_pk_add_f32 v[32:33], v[32:33], v[44:45]
	s_waitcnt lgkmcnt(3)
	v_pk_add_f32 v[34:35], v[34:35], v[50:51]
	v_pk_add_f32 v[32:33], v[32:33], v[48:49]
	s_waitcnt lgkmcnt(2)
	v_pk_add_f32 v[34:35], v[34:35], v[54:55]
	v_pk_add_f32 v[32:33], v[32:33], v[52:53]
	s_waitcnt lgkmcnt(1)
	v_pk_add_f32 v[34:35], v[34:35], v[58:59]
	v_pk_add_f32 v[32:33], v[32:33], v[56:57]
	s_waitcnt lgkmcnt(0)
	v_pk_add_f32 v[34:35], v[34:35], v[62:63]
	v_pk_add_f32 v[32:33], v[32:33], v[60:61]
	s_waitcnt vmcnt(0)
	v_pk_add_f32 v[34:35], v[34:35], v[70:71]
	v_pk_add_f32 v[32:33], v[32:33], v[68:69]
	v_mul_f32_e32 v75, v35, v35
	v_mul_f32_e32 v74, v33, v33
	v_fmac_f32_e32 v74, v32, v32
	v_fmac_f32_e32 v75, v34, v34
	v_add_f32_e32 v76, v74, v75
	v_xor_b32_e32 v77, 16, v23
	v_lshlrev_b32_e32 v77, 2, v77
	ds_bpermute_b32 v78, v77, v76
	v_cvt_pk_bf16_f32 v80, v32, v33
	v_cvt_pk_bf16_f32 v81, v34, v35
	v_xor_b32_e32 v79, 32, v23
	v_lshlrev_b32_e32 v79, 2, v79
	s_waitcnt lgkmcnt(0)
	v_add_f32_e32 v76, v76, v78
	ds_bpermute_b32 v78, v79, v76
	global_store_dwordx2 v65, v[80:81], s[8:9]
	v_lshlrev_b32_e32 v82, 2, v28
	v_cmp_gt_u32_e32 vcc, 16, v23
	s_waitcnt lgkmcnt(0)
	v_add_f32_e32 v76, v76, v78
	s_and_saveexec_b64 s[10:11], vcc
	s_add_u32 s4, s92, 0x10400
	s_addc_u32 s5, s93, 0
	s_nop 0
	global_atomic_add_f32 v82, v76, s[4:5]
	s_add_u32 s4, s92, 0x8000
	s_addc_u32 s5, s93, 0
	s_mov_b64 exec, s[10:11]

.Lsk_p6_loop:
	s_cmpk_lt_i32 s18, 0x100
	s_cbranch_scc0 .Lsk_p6_done
	s_and_b32 s20, s18, 7
	s_lshr_b32 s22, s18, 5
	s_lshl_b32 s22, s22, 3
	s_or_b32 s20, s20, s22
	s_bfe_u32 s21, s18, 0x20003
	s_lshl_b32 s22, s21, 5
	v_add_u32_e32 v28, s22, v21
	s_mul_i32 s23, s19, 0x80
	v_mul_u32_u24_e32 v16, 0x400, v28
	v_add_u32_e32 v16, s23, v16
	v_lshl_add_u32 v16, v22, 4, v16
	v_add_u32_e32 v17, 0x4000, v16
	s_lshl_b32 s22, s20, 5
	v_add_u32_e32 v29, s22, v21
	v_mul_u32_u24_e32 v18, 0x400, v29
	v_add_u32_e32 v18, s23, v18
	v_lshl_add_u32 v18, v22, 4, v18
	v_add_u32_e32 v19, 0x4000, v18
	global_load_dwordx4 v[32:35], v18, s[4:5] offset:0
	global_load_dwordx4 v[36:39], v19, s[4:5] offset:0
	global_load_dwordx4 v[40:43], v18, s[4:5] offset:64
	global_load_dwordx4 v[44:47], v19, s[4:5] offset:64
	global_load_dwordx4 v[112:115], v16, s[0:1] offset:0
	global_load_dwordx4 v[116:119], v17, s[0:1] offset:0
	global_load_dwordx4 v[120:123], v16, s[0:1] offset:64
	global_load_dwordx4 v[124:127], v17, s[0:1] offset:64
	s_waitcnt vmcnt(3)
	v_mfma_f32_16x16x32_bf16 v[0:3], v[32:35], v[112:115], 0
	s_waitcnt vmcnt(2)
	v_mfma_f32_16x16x32_bf16 v[4:7], v[32:35], v[116:119], 0
	v_mfma_f32_16x16x32_bf16 v[8:11], v[36:39], v[112:115], 0
	v_mfma_f32_16x16x32_bf16 v[12:15], v[36:39], v[116:119], 0
	s_waitcnt vmcnt(1)
	v_mfma_f32_16x16x32_bf16 v[0:3], v[40:43], v[120:123], v[0:3]
	s_waitcnt vmcnt(0)
	v_mfma_f32_16x16x32_bf16 v[4:7], v[40:43], v[124:127], v[4:7]
	v_mfma_f32_16x16x32_bf16 v[8:11], v[44:47], v[120:123], v[8:11]
	v_mfma_f32_16x16x32_bf16 v[12:15], v[44:47], v[124:127], v[12:15]
	s_lshl_b32 s22, s19, 12
	v_lshl_add_u32 v31, v23, 4, s22
	s_nop 7
	s_nop 3
	ds_write_b128 v31, v[0:3]
	ds_write_b128 v31, v[4:7] offset:1024
	ds_write_b128 v31, v[8:11] offset:2048
	ds_write_b128 v31, v[12:15] offset:3072
	s_lshl_b32 s22, s21, 5
	s_and_b32 s23, s19, 1
	s_lshl_b32 s23, s23, 4
	s_add_i32 s22, s22, s23
	v_add_u32_e32 v28, s22, v21
	s_lshl_b32 s23, s20, 5
	s_lshr_b32 s22, s19, 1
	s_lshl_b32 s22, s22, 4
	s_add_i32 s23, s23, s22
	v_lshl_add_u32 v29, v22, 2, s23
	v_lshl_add_u32 v29, v28, 11, v29
	s_lshl_b32 s22, s19, 10
	v_lshl_add_u32 v30, v23, 4, s22
	s_waitcnt lgkmcnt(0)
	s_barrier
	s_cmp_lt_u32 s19, 4
	s_cbranch_scc0 .Lsk_p6_skip
	v_lshlrev_b32_e32 v65, 1, v29
	global_load_dwordx2 v[72:73], v65, s[12:13]
	v_lshlrev_b32_e32 v64, 2, v29
	ds_read_b128 v[32:35], v30
	ds_read_b128 v[36:39], v30 offset:4096
	ds_read_b128 v[40:43], v30 offset:8192
	ds_read_b128 v[44:47], v30 offset:12288
	ds_read_b128 v[48:51], v30 offset:16384
	ds_read_b128 v[52:55], v30 offset:20480
	ds_read_b128 v[56:59], v30 offset:24576
	ds_read_b128 v[60:63], v30 offset:28672
	s_waitcnt lgkmcnt(7)
	v_pk_add_f32 v[34:35], v[34:35], 0 op_sel_hi:[1,0]
	v_pk_add_f32 v[32:33], v[32:33], 0 op_sel_hi:[1,0]
	s_waitcnt lgkmcnt(6)
	v_pk_add_f32 v[34:35], v[34:35], v[38:39]
	v_pk_add_f32 v[32:33], v[32:33], v[36:37]
	s_waitcnt lgkmcnt(5)
	v_pk_add_f32 v[34:35], v[34:35], v[42:43]
	v_pk_add_f32 v[32:33], v[32:33], v[40:41]
	s_waitcnt lgkmcnt(4)
	v_pk_add_f32 v[34:35], v[34:35], v[46:47]
	v_pk_add_f32 v[32:33], v[32:33], v[44:45]
	s_waitcnt lgkmcnt(3)
	v_pk_add_f32 v[34:35], v[34:35], v[50:51]
	v_pk_add_f32 v[32:33], v[32:33], v[48:49]
	s_waitcnt lgkmcnt(2)
	v_pk_add_f32 v[34:35], v[34:35], v[54:55]
	v_pk_add_f32 v[32:33], v[32:33], v[52:53]
	s_waitcnt lgkmcnt(1)
	v_pk_add_f32 v[34:35], v[34:35], v[58:59]
	v_pk_add_f32 v[32:33], v[32:33], v[56:57]
	s_waitcnt lgkmcnt(0)
	v_pk_add_f32 v[34:35], v[34:35], v[62:63]
	v_pk_add_f32 v[32:33], v[32:33], v[60:61]
	s_waitcnt vmcnt(0)
	v_lshlrev_b32_e32 v68, 16, v72
	v_and_b32_e32 v69, 0xffff0000, v72
	v_lshlrev_b32_e32 v70, 16, v73
	v_and_b32_e32 v71, 0xffff0000, v73
	v_pk_add_f32 v[34:35], v[34:35], v[70:71]
	v_pk_add_f32 v[32:33], v[32:33], v[68:69]
	v_mul_f32_e32 v75, v35, v35
	v_mul_f32_e32 v74, v33, v33
	v_fmac_f32_e32 v74, v32, v32
	v_fmac_f32_e32 v75, v34, v34
	v_add_f32_e32 v76, v74, v75
	v_xor_b32_e32 v77, 16, v23
	v_lshlrev_b32_e32 v77, 2, v77
	ds_bpermute_b32 v78, v77, v76
	v_cvt_pk_bf16_f32 v80, v32, v33
	v_cvt_pk_bf16_f32 v81, v34, v35
	v_xor_b32_e32 v79, 32, v23
	v_lshlrev_b32_e32 v79, 2, v79
	s_waitcnt lgkmcnt(0)
	v_add_f32_e32 v76, v76, v78
	ds_bpermute_b32 v78, v79, v76
	global_store_dwordx2 v65, v[80:81], s[12:13]
	v_lshlrev_b32_e32 v82, 2, v28
	v_cmp_gt_u32_e32 vcc, 16, v23
	s_waitcnt lgkmcnt(0)
	v_add_f32_e32 v76, v76, v78
	s_and_saveexec_b64 s[16:17], vcc
	global_atomic_add_f32 v82, v76, s[14:15]
	s_mov_b64 exec, s[16:17]

.Lsk_p9_loop:
	s_cmpk_lt_i32 s16, 0x100
	s_cbranch_scc0 .Lsk_p9_done
	s_and_b32 s18, s16, 7
	s_lshr_b32 s20, s16, 5
	s_lshl_b32 s20, s20, 3
	s_or_b32 s18, s18, s20
	s_bfe_u32 s19, s16, 0x20003
	s_lshl_b32 s20, s19, 5
	v_add_u32_e32 v28, s20, v21
	s_mul_i32 s21, s17, 0x580
	v_mul_u32_u24_e32 v16, 0x2c00, v28
	v_add_u32_e32 v16, s21, v16
	v_lshl_add_u32 v16, v22, 4, v16
	v_add_u32_e32 v17, 0x2c000, v16
	s_lshl_b32 s20, s18, 5
	v_add_u32_e32 v29, s20, v21
	v_mul_u32_u24_e32 v18, 0x2c00, v29
	v_add_u32_e32 v18, s21, v18
	v_lshl_add_u32 v18, v22, 4, v18
	v_add_u32_e32 v19, 0x2c000, v18
	global_load_dwordx4 v[32:35], v18, s[2:3] offset:0
	global_load_dwordx4 v[36:39], v19, s[2:3] offset:0
	global_load_dwordx4 v[40:43], v18, s[2:3] offset:64
	global_load_dwordx4 v[44:47], v19, s[2:3] offset:64
	global_load_dwordx4 v[48:51], v18, s[2:3] offset:128
	global_load_dwordx4 v[52:55], v19, s[2:3] offset:128
	global_load_dwordx4 v[56:59], v18, s[2:3] offset:192
	global_load_dwordx4 v[60:63], v19, s[2:3] offset:192
	global_load_dwordx4 v[64:67], v18, s[2:3] offset:256
	global_load_dwordx4 v[68:71], v19, s[2:3] offset:256
	global_load_dwordx4 v[72:75], v18, s[2:3] offset:320
	global_load_dwordx4 v[76:79], v19, s[2:3] offset:320
	global_load_dwordx4 v[80:83], v18, s[2:3] offset:384
	global_load_dwordx4 v[84:87], v19, s[2:3] offset:384
	global_load_dwordx4 v[88:91], v18, s[2:3] offset:448
	global_load_dwordx4 v[92:95], v19, s[2:3] offset:448
	global_load_dwordx4 v[96:99], v18, s[2:3] offset:512
	global_load_dwordx4 v[100:103], v19, s[2:3] offset:512
	global_load_dwordx4 v[104:107], v18, s[2:3] offset:576
	global_load_dwordx4 v[108:111], v19, s[2:3] offset:576
	global_load_dwordx4 v[112:115], v16, s[0:1] offset:0
	global_load_dwordx4 v[116:119], v17, s[0:1] offset:0
	global_load_dwordx4 v[120:123], v16, s[0:1] offset:64
	global_load_dwordx4 v[124:127], v17, s[0:1] offset:64
	global_load_dwordx4 v[174:177], v16, s[0:1] offset:128
	global_load_dwordx4 v[178:181], v17, s[0:1] offset:128
	global_load_dwordx4 v[182:185], v16, s[0:1] offset:192
	global_load_dwordx4 v[186:189], v17, s[0:1] offset:192
	global_load_dwordx4 v[190:193], v16, s[0:1] offset:256
	global_load_dwordx4 v[194:197], v17, s[0:1] offset:256
	global_load_dwordx4 v[198:201], v16, s[0:1] offset:320
	global_load_dwordx4 v[202:205], v17, s[0:1] offset:320
	s_waitcnt vmcnt(11)
	v_mfma_f32_16x16x32_bf16 v[0:3], v[32:35], v[112:115], 0
	s_waitcnt vmcnt(10)
	v_mfma_f32_16x16x32_bf16 v[4:7], v[32:35], v[116:119], 0
	v_mfma_f32_16x16x32_bf16 v[8:11], v[36:39], v[112:115], 0
	v_mfma_f32_16x16x32_bf16 v[12:15], v[36:39], v[116:119], 0
	global_load_dwordx4 v[112:115], v16, s[0:1] offset:384
	global_load_dwordx4 v[116:119], v17, s[0:1] offset:384
	global_load_dwordx4 v[32:35], v18, s[2:3] offset:640
	global_load_dwordx4 v[36:39], v19, s[2:3] offset:640
	s_waitcnt vmcnt(13)
	v_mfma_f32_16x16x32_bf16 v[0:3], v[40:43], v[120:123], v[0:3]
	s_waitcnt vmcnt(12)
	v_mfma_f32_16x16x32_bf16 v[4:7], v[40:43], v[124:127], v[4:7]
	v_mfma_f32_16x16x32_bf16 v[8:11], v[44:47], v[120:123], v[8:11]
	v_mfma_f32_16x16x32_bf16 v[12:15], v[44:47], v[124:127], v[12:15]
	global_load_dwordx4 v[120:123], v16, s[0:1] offset:448
	global_load_dwordx4 v[124:127], v17, s[0:1] offset:448
	global_load_dwordx4 v[40:43], v18, s[2:3] offset:704
	global_load_dwordx4 v[44:47], v19, s[2:3] offset:704
	s_waitcnt vmcnt(15)
	v_mfma_f32_16x16x32_bf16 v[0:3], v[48:51], v[174:177], v[0:3]
	s_waitcnt vmcnt(14)
	v_mfma_f32_16x16x32_bf16 v[4:7], v[48:51], v[178:181], v[4:7]
	v_mfma_f32_16x16x32_bf16 v[8:11], v[52:55], v[174:177], v[8:11]
	v_mfma_f32_16x16x32_bf16 v[12:15], v[52:55], v[178:181], v[12:15]
	global_load_dwordx4 v[174:177], v16, s[0:1] offset:512
	global_load_dwordx4 v[178:181], v17, s[0:1] offset:512
	global_load_dwordx4 v[48:51], v18, s[2:3] offset:768
	global_load_dwordx4 v[52:55], v19, s[2:3] offset:768
	s_waitcnt vmcnt(17)
	v_mfma_f32_16x16x32_bf16 v[0:3], v[56:59], v[182:185], v[0:3]
	s_waitcnt vmcnt(16)
	v_mfma_f32_16x16x32_bf16 v[4:7], v[56:59], v[186:189], v[4:7]
	v_mfma_f32_16x16x32_bf16 v[8:11], v[60:63], v[182:185], v[8:11]
	v_mfma_f32_16x16x32_bf16 v[12:15], v[60:63], v[186:189], v[12:15]
	global_load_dwordx4 v[182:185], v16, s[0:1] offset:576
	global_load_dwordx4 v[186:189], v17, s[0:1] offset:576
	global_load_dwordx4 v[56:59], v18, s[2:3] offset:832
	global_load_dwordx4 v[60:63], v19, s[2:3] offset:832
	s_waitcnt vmcnt(19)
	v_mfma_f32_16x16x32_bf16 v[0:3], v[64:67], v[190:193], v[0:3]
	s_waitcnt vmcnt(18)
	v_mfma_f32_16x16x32_bf16 v[4:7], v[64:67], v[194:197], v[4:7]
	v_mfma_f32_16x16x32_bf16 v[8:11], v[68:71], v[190:193], v[8:11]
	v_mfma_f32_16x16x32_bf16 v[12:15], v[68:71], v[194:197], v[12:15]
	global_load_dwordx4 v[190:193], v16, s[0:1] offset:640
	global_load_dwordx4 v[194:197], v17, s[0:1] offset:640
	global_load_dwordx4 v[64:67], v18, s[2:3] offset:896
	global_load_dwordx4 v[68:71], v19, s[2:3] offset:896
	s_waitcnt vmcnt(21)
	v_mfma_f32_16x16x32_bf16 v[0:3], v[72:75], v[198:201], v[0:3]
	s_waitcnt vmcnt(20)
	v_mfma_f32_16x16x32_bf16 v[4:7], v[72:75], v[202:205], v[4:7]
	v_mfma_f32_16x16x32_bf16 v[8:11], v[76:79], v[198:201], v[8:11]
	v_mfma_f32_16x16x32_bf16 v[12:15], v[76:79], v[202:205], v[12:15]
	global_load_dwordx4 v[198:201], v16, s[0:1] offset:704
	global_load_dwordx4 v[202:205], v17, s[0:1] offset:704
	global_load_dwordx4 v[72:75], v18, s[2:3] offset:960
	global_load_dwordx4 v[76:79], v19, s[2:3] offset:960
	s_waitcnt vmcnt(23)
	v_mfma_f32_16x16x32_bf16 v[0:3], v[80:83], v[112:115], v[0:3]
	s_waitcnt vmcnt(22)
	v_mfma_f32_16x16x32_bf16 v[4:7], v[80:83], v[116:119], v[4:7]
	v_mfma_f32_16x16x32_bf16 v[8:11], v[84:87], v[112:115], v[8:11]
	v_mfma_f32_16x16x32_bf16 v[12:15], v[84:87], v[116:119], v[12:15]
	global_load_dwordx4 v[112:115], v16, s[0:1] offset:768
	global_load_dwordx4 v[116:119], v17, s[0:1] offset:768
	global_load_dwordx4 v[80:83], v18, s[2:3] offset:1024
	global_load_dwordx4 v[84:87], v19, s[2:3] offset:1024
	s_waitcnt vmcnt(23)
	v_mfma_f32_16x16x32_bf16 v[0:3], v[88:91], v[120:123], v[0:3]
	s_waitcnt vmcnt(22)
	v_mfma_f32_16x16x32_bf16 v[4:7], v[88:91], v[124:127], v[4:7]
	v_mfma_f32_16x16x32_bf16 v[8:11], v[92:95], v[120:123], v[8:11]
	v_mfma_f32_16x16x32_bf16 v[12:15], v[92:95], v[124:127], v[12:15]
	global_load_dwordx4 v[120:123], v16, s[0:1] offset:832
	global_load_dwordx4 v[124:127], v17, s[0:1] offset:832
	global_load_dwordx4 v[88:91], v18, s[2:3] offset:1088
	global_load_dwordx4 v[92:95], v19, s[2:3] offset:1088
	s_waitcnt vmcnt(23)
	v_mfma_f32_16x16x32_bf16 v[0:3], v[96:99], v[174:177], v[0:3]
	s_waitcnt vmcnt(22)
	v_mfma_f32_16x16x32_bf16 v[4:7], v[96:99], v[178:181], v[4:7]
	v_mfma_f32_16x16x32_bf16 v[8:11], v[100:103], v[174:177], v[8:11]
	v_mfma_f32_16x16x32_bf16 v[12:15], v[100:103], v[178:181], v[12:15]
	global_load_dwordx4 v[174:177], v16, s[0:1] offset:896
	global_load_dwordx4 v[178:181], v17, s[0:1] offset:896
	global_load_dwordx4 v[96:99], v18, s[2:3] offset:1152
	global_load_dwordx4 v[100:103], v19, s[2:3] offset:1152
	s_waitcnt vmcnt(23)
	v_mfma_f32_16x16x32_bf16 v[0:3], v[104:107], v[182:185], v[0:3]
	s_waitcnt vmcnt(22)
	v_mfma_f32_16x16x32_bf16 v[4:7], v[104:107], v[186:189], v[4:7]
	v_mfma_f32_16x16x32_bf16 v[8:11], v[108:111], v[182:185], v[8:11]
	v_mfma_f32_16x16x32_bf16 v[12:15], v[108:111], v[186:189], v[12:15]
	global_load_dwordx4 v[182:185], v16, s[0:1] offset:960
	global_load_dwordx4 v[186:189], v17, s[0:1] offset:960
	global_load_dwordx4 v[104:107], v18, s[2:3] offset:1216
	global_load_dwordx4 v[108:111], v19, s[2:3] offset:1216
	s_waitcnt vmcnt(23)
	v_mfma_f32_16x16x32_bf16 v[0:3], v[32:35], v[190:193], v[0:3]
	s_waitcnt vmcnt(22)
	v_mfma_f32_16x16x32_bf16 v[4:7], v[32:35], v[194:197], v[4:7]
	v_mfma_f32_16x16x32_bf16 v[8:11], v[36:39], v[190:193], v[8:11]
	v_mfma_f32_16x16x32_bf16 v[12:15], v[36:39], v[194:197], v[12:15]
	global_load_dwordx4 v[190:193], v16, s[0:1] offset:1024
	global_load_dwordx4 v[194:197], v17, s[0:1] offset:1024
	global_load_dwordx4 v[32:35], v18, s[2:3] offset:1280
	global_load_dwordx4 v[36:39], v19, s[2:3] offset:1280
	s_waitcnt vmcnt(23)
	v_mfma_f32_16x16x32_bf16 v[0:3], v[40:43], v[198:201], v[0:3]
	s_waitcnt vmcnt(22)
	v_mfma_f32_16x16x32_bf16 v[4:7], v[40:43], v[202:205], v[4:7]
	v_mfma_f32_16x16x32_bf16 v[8:11], v[44:47], v[198:201], v[8:11]
	v_mfma_f32_16x16x32_bf16 v[12:15], v[44:47], v[202:205], v[12:15]
	global_load_dwordx4 v[198:201], v16, s[0:1] offset:1088
	global_load_dwordx4 v[202:205], v17, s[0:1] offset:1088
	global_load_dwordx4 v[40:43], v18, s[2:3] offset:1344
	global_load_dwordx4 v[44:47], v19, s[2:3] offset:1344
	s_waitcnt vmcnt(23)
	v_mfma_f32_16x16x32_bf16 v[0:3], v[48:51], v[112:115], v[0:3]
	s_waitcnt vmcnt(22)
	v_mfma_f32_16x16x32_bf16 v[4:7], v[48:51], v[116:119], v[4:7]
	v_mfma_f32_16x16x32_bf16 v[8:11], v[52:55], v[112:115], v[8:11]
	v_mfma_f32_16x16x32_bf16 v[12:15], v[52:55], v[116:119], v[12:15]
	global_load_dwordx4 v[112:115], v16, s[0:1] offset:1152
	global_load_dwordx4 v[116:119], v17, s[0:1] offset:1152
	s_waitcnt vmcnt(21)
	v_mfma_f32_16x16x32_bf16 v[0:3], v[56:59], v[120:123], v[0:3]
	s_waitcnt vmcnt(20)
	v_mfma_f32_16x16x32_bf16 v[4:7], v[56:59], v[124:127], v[4:7]
	v_mfma_f32_16x16x32_bf16 v[8:11], v[60:63], v[120:123], v[8:11]
	v_mfma_f32_16x16x32_bf16 v[12:15], v[60:63], v[124:127], v[12:15]
	global_load_dwordx4 v[120:123], v16, s[0:1] offset:1216
	global_load_dwordx4 v[124:127], v17, s[0:1] offset:1216
	s_waitcnt vmcnt(19)
	v_mfma_f32_16x16x32_bf16 v[0:3], v[64:67], v[174:177], v[0:3]
	s_waitcnt vmcnt(18)
	v_mfma_f32_16x16x32_bf16 v[4:7], v[64:67], v[178:181], v[4:7]
	v_mfma_f32_16x16x32_bf16 v[8:11], v[68:71], v[174:177], v[8:11]
	v_mfma_f32_16x16x32_bf16 v[12:15], v[68:71], v[178:181], v[12:15]
	global_load_dwordx4 v[174:177], v16, s[0:1] offset:1280
	global_load_dwordx4 v[178:181], v17, s[0:1] offset:1280
	s_waitcnt vmcnt(17)
	v_mfma_f32_16x16x32_bf16 v[0:3], v[72:75], v[182:185], v[0:3]
	s_waitcnt vmcnt(16)
	v_mfma_f32_16x16x32_bf16 v[4:7], v[72:75], v[186:189], v[4:7]
	v_mfma_f32_16x16x32_bf16 v[8:11], v[76:79], v[182:185], v[8:11]
	v_mfma_f32_16x16x32_bf16 v[12:15], v[76:79], v[186:189], v[12:15]
	global_load_dwordx4 v[182:185], v16, s[0:1] offset:1344
	global_load_dwordx4 v[186:189], v17, s[0:1] offset:1344
	s_waitcnt vmcnt(15)
	v_mfma_f32_16x16x32_bf16 v[0:3], v[80:83], v[190:193], v[0:3]
	s_waitcnt vmcnt(14)
	v_mfma_f32_16x16x32_bf16 v[4:7], v[80:83], v[194:197], v[4:7]
	v_mfma_f32_16x16x32_bf16 v[8:11], v[84:87], v[190:193], v[8:11]
	v_mfma_f32_16x16x32_bf16 v[12:15], v[84:87], v[194:197], v[12:15]
	s_waitcnt vmcnt(11)
	v_mfma_f32_16x16x32_bf16 v[0:3], v[88:91], v[198:201], v[0:3]
	s_waitcnt vmcnt(10)
	v_mfma_f32_16x16x32_bf16 v[4:7], v[88:91], v[202:205], v[4:7]
	v_mfma_f32_16x16x32_bf16 v[8:11], v[92:95], v[198:201], v[8:11]
	v_mfma_f32_16x16x32_bf16 v[12:15], v[92:95], v[202:205], v[12:15]
	s_waitcnt vmcnt(7)
	v_mfma_f32_16x16x32_bf16 v[0:3], v[96:99], v[112:115], v[0:3]
	s_waitcnt vmcnt(6)
	v_mfma_f32_16x16x32_bf16 v[4:7], v[96:99], v[116:119], v[4:7]
	v_mfma_f32_16x16x32_bf16 v[8:11], v[100:103], v[112:115], v[8:11]
	v_mfma_f32_16x16x32_bf16 v[12:15], v[100:103], v[116:119], v[12:15]
	s_waitcnt vmcnt(5)
	v_mfma_f32_16x16x32_bf16 v[0:3], v[104:107], v[120:123], v[0:3]
	s_waitcnt vmcnt(4)
	v_mfma_f32_16x16x32_bf16 v[4:7], v[104:107], v[124:127], v[4:7]
	v_mfma_f32_16x16x32_bf16 v[8:11], v[108:111], v[120:123], v[8:11]
	v_mfma_f32_16x16x32_bf16 v[12:15], v[108:111], v[124:127], v[12:15]
	s_waitcnt vmcnt(3)
	v_mfma_f32_16x16x32_bf16 v[0:3], v[32:35], v[174:177], v[0:3]
	s_waitcnt vmcnt(2)
	v_mfma_f32_16x16x32_bf16 v[4:7], v[32:35], v[178:181], v[4:7]
	v_mfma_f32_16x16x32_bf16 v[8:11], v[36:39], v[174:177], v[8:11]
	v_mfma_f32_16x16x32_bf16 v[12:15], v[36:39], v[178:181], v[12:15]
	s_waitcnt vmcnt(1)
	v_mfma_f32_16x16x32_bf16 v[0:3], v[40:43], v[182:185], v[0:3]
	s_waitcnt vmcnt(0)
	v_mfma_f32_16x16x32_bf16 v[4:7], v[40:43], v[186:189], v[4:7]
	v_mfma_f32_16x16x32_bf16 v[8:11], v[44:47], v[182:185], v[8:11]
	v_mfma_f32_16x16x32_bf16 v[12:15], v[44:47], v[186:189], v[12:15]
	s_lshl_b32 s20, s17, 12
	v_lshl_add_u32 v31, v23, 4, s20
	s_nop 7
	s_nop 3
	ds_write_b128 v31, v[0:3]
	ds_write_b128 v31, v[4:7] offset:1024
	ds_write_b128 v31, v[8:11] offset:2048
	ds_write_b128 v31, v[12:15] offset:3072
	s_lshl_b32 s20, s19, 5
	s_and_b32 s21, s17, 1
	s_lshl_b32 s21, s21, 4
	s_add_i32 s20, s20, s21
	v_add_u32_e32 v28, s20, v21
	s_lshl_b32 s21, s18, 5
	s_lshr_b32 s20, s17, 1
	s_lshl_b32 s20, s20, 4
	s_add_i32 s21, s21, s20
	v_lshl_add_u32 v29, v22, 2, s21
	v_lshl_add_u32 v29, v28, 11, v29
	s_lshl_b32 s20, s17, 10
	v_lshl_add_u32 v30, v23, 4, s20
	s_waitcnt lgkmcnt(0)
	s_barrier
	s_cmp_lt_u32 s17, 4
	s_cbranch_scc0 .Lsk_p9_skip
	v_lshlrev_b32_e32 v65, 1, v29
	global_load_dwordx2 v[72:73], v65, s[10:11]
	v_lshlrev_b32_e32 v64, 2, v29
	ds_read_b128 v[32:35], v30
	ds_read_b128 v[36:39], v30 offset:4096
	ds_read_b128 v[40:43], v30 offset:8192
	ds_read_b128 v[44:47], v30 offset:12288
	ds_read_b128 v[48:51], v30 offset:16384
	ds_read_b128 v[52:55], v30 offset:20480
	ds_read_b128 v[56:59], v30 offset:24576
	ds_read_b128 v[60:63], v30 offset:28672
	s_waitcnt lgkmcnt(7)
	v_pk_add_f32 v[34:35], v[34:35], 0 op_sel_hi:[1,0]
	v_pk_add_f32 v[32:33], v[32:33], 0 op_sel_hi:[1,0]
	s_waitcnt lgkmcnt(6)
	v_pk_add_f32 v[34:35], v[34:35], v[38:39]
	v_pk_add_f32 v[32:33], v[32:33], v[36:37]
	s_waitcnt lgkmcnt(5)
	v_pk_add_f32 v[34:35], v[34:35], v[42:43]
	v_pk_add_f32 v[32:33], v[32:33], v[40:41]
	s_waitcnt lgkmcnt(4)
	v_pk_add_f32 v[34:35], v[34:35], v[46:47]
	v_pk_add_f32 v[32:33], v[32:33], v[44:45]
	s_waitcnt lgkmcnt(3)
	v_pk_add_f32 v[34:35], v[34:35], v[50:51]
	v_pk_add_f32 v[32:33], v[32:33], v[48:49]
	s_waitcnt lgkmcnt(2)
	v_pk_add_f32 v[34:35], v[34:35], v[54:55]
	v_pk_add_f32 v[32:33], v[32:33], v[52:53]
	s_waitcnt lgkmcnt(1)
	v_pk_add_f32 v[34:35], v[34:35], v[58:59]
	v_pk_add_f32 v[32:33], v[32:33], v[56:57]
	s_waitcnt lgkmcnt(0)
	v_pk_add_f32 v[34:35], v[34:35], v[62:63]
	v_pk_add_f32 v[32:33], v[32:33], v[60:61]
	s_waitcnt vmcnt(0)
	v_lshlrev_b32_e32 v68, 16, v72
	v_and_b32_e32 v69, 0xffff0000, v72
	v_lshlrev_b32_e32 v70, 16, v73
	v_and_b32_e32 v71, 0xffff0000, v73
	v_pk_add_f32 v[34:35], v[34:35], v[70:71]
	v_pk_add_f32 v[32:33], v[32:33], v[68:69]
	global_store_dwordx4 v64, v[32:35], s[12:13]
